# attention prompt path: redundant loop-top barrier skipped (bounce barrier already orders the tile), bounce LDS addresses computed once per item
# baseline (speedup 1.0000x reference)
; #define LAS __attribute__((address_space(3)))
; __device__ __forceinline__ int fresh_tid(int wv) { int t = (wv << 6) | lane_id(); asm volatile("" : "+v"(t)); return t; }
; __device__ __forceinline__ void attn_item(const Params& P, int l, LAS unsigned char* lds, int item, const int wv) {
;     const int tid = fresh_tid(wv), w = tid >> 6, lane = tid & 63, fr = lane & 15, fq = lane >> 4, hw = w >> 2, qw = w & 3;
;     const bf16_t* proj = (const bf16_t*)(P.ws + WS_R1);
;     const bool smp = item >= 512;
;     int hp, q0, nq, kbase, nkt, qpos0, kpos0, s = 0;
;     if (!smp) { const int c = item >> 2; hp = item & 3; q0 = 64 * c; nq = 64; const int c0 = c > 8 ? c - 8 : 0; kbase = 64 * c0; nkt = c - c0 + 1; qpos0 = q0; kpos0 = kbase; }
;     else { const int it = item - 512; s = it >> 2; hp = it & 3; q0 = TP + 16 * s; nq = 16; kbase = 0; nkt = 9; qpos0 = 1024; kpos0 = 512; }
;     const int head = 2 * hp + hw;
;     const bool active = 16 * qw < nq;
;     LAS bf16_t* Kl = (LAS bf16_t*)(lds + AT_K); LAS bf16_t* Vt = (LAS bf16_t*)(lds + AT_V); LAS float* Bs = (LAS float*)(lds + AT_B);
;     __syncthreads();
;     for (int i = tid; i < 2 * 257; i += 512) { const int hh = i / 257, j = i - hh * 257; Bs[hh * 260 + j] = P.relb[((size_t)l * 8 + 2 * hp + hh) * 257 + j]; }
;     bf16x8 qf[4];
;     { const int row = q0 + 16 * qw + fr;
; #pragma unroll
;       for (int ks = 0; ks < 4; ++ks) qf[ks] = active ? *(const bf16x8*)(proj + (size_t)row * NIN + head * 128 + 32 * ks + 8 * fq) : (bf16x8){0, 0, 0, 0, 0, 0, 0, 0}; }
;     f32x4 oacc[8];
; #pragma unroll
;     for (int d = 0; d < 8; ++d) oacc[d] = (f32x4){0.f, 0.f, 0.f, 0.f};
;     float m_run = -INFINITY, l_run = 0.f;
;     const float scale = 0.08838834764831845f;
;     u32x4 kreg[4], vreg[4];
;     ...
;     ATT_LOAD(0);
;     for (int jt = 0; jt < nkt; ++jt) {
;         __syncthreads();
.LBB0_351:
	v_lshlrev_b32_e32 v8, 2, v50
	v_and_b32_e32 v8, 64, v8
	v_lshlrev_b32_e32 v62, 3, v50
	v_and_b32_e32 v114, 63, v50
	v_lshl_add_u32 v69, v54, 4, 16
	v_lshlrev_b32_e32 v101, 2, v54
	v_mov_b32_e32 v54, s7
	v_lshrrev_b32_e32 v50, 3, v50
	v_mad_i32_i24 v113, v53, s42, v54
	v_add_u32_e32 v54, v8, v102
	s_movk_i32 s21, 0x110
	v_and_b32_e32 v50, 0x78, v50
	s_mov_b32 s14, 0xfffff80
	v_mul_lo_u32 v71, v54, s21
	v_and_or_b32 v54, v60, s14, v50
	s_movk_i32 s19, 0x90
	v_mul_lo_u32 v60, v54, s19
	v_add_u32_e32 v54, v106, v8
	v_mul_lo_u32 v72, v54, s21
	v_lshrrev_b32_e32 v54, 3, v59
	v_and_b32_e32 v54, 0x78, v54
	v_and_or_b32 v54, v57, s14, v54
	v_mul_lo_u32 v59, v54, s19
	v_add_u32_e32 v54, v108, v8
	v_add_u32_e32 v8, v110, v8
	v_mul_lo_u32 v74, v8, s21
	v_lshrrev_b32_e32 v8, 3, v58
	s_lshl_b32 s8, s29, 4
	v_and_b32_e32 v8, 0x78, v8
	s_add_i32 s18, s8, 0x2000
	v_and_or_b32 v8, v55, s14, v8
	v_and_b32_e32 v67, 0xf8, v62
	v_mov_b64_e32 v[62:63], s[30:31]
	v_mul_lo_u32 v58, v8, s19
	v_add_u32_e32 v8, s18, v102
	s_lshl_b32 s82, s28, 8
	v_mul_lo_u32 v73, v54, s21
	v_and_or_b32 v50, v56, s14, v50
	v_and_b32_e32 v120, -8, v55
	v_mad_i64_i32 v[54:55], s[14:15], v8, s13, v[62:63]
	v_lshl_add_u64 v[54:55], v[54:55], 0, s[82:83]
	v_lshlrev_b32_e32 v8, 1, v67
	v_lshl_add_u64 v[122:123], v[54:55], 0, v[8:9]
	v_add_u32_e32 v54, s18, v106
	v_mad_i64_i32 v[54:55], s[14:15], v54, s13, v[62:63]
	v_lshl_add_u64 v[54:55], v[54:55], 0, s[82:83]
	v_lshl_add_u64 v[126:127], v[54:55], 0, v[8:9]
	v_add_u32_e32 v54, s18, v108
	v_or_b32_e32 v64, s18, v114
	v_mad_i64_i32 v[54:55], s[14:15], v54, s13, v[62:63]
	v_mad_u64_u32 v[64:65], s[8:9], v64, s13, v[62:63]
	v_lshl_add_u64 v[54:55], v[54:55], 0, s[82:83]
	v_lshl_add_u64 v[64:65], v[64:65], 0, s[82:83]
	s_mov_b64 s[8:9], 0x1000
	v_lshl_add_u64 v[130:131], v[54:55], 0, v[8:9]
	v_add_u32_e32 v54, s18, v110
	v_lshl_add_u64 v[64:65], v[64:65], 0, s[8:9]
	s_add_i32 s8, s29, s24
	s_mov_b32 s9, s83
	v_mad_i64_i32 v[54:55], s[14:15], v54, s13, v[62:63]
	v_readlane_b32 s52, v252, 36
	s_lshl_b32 s20, s28, 7
	s_lshl_b64 s[8:9], s[8:9], 9
	s_lshl_b32 s14, s28, 9
	v_readlane_b32 s58, v252, 42
	v_readlane_b32 s59, v252, 43
	s_add_u32 s28, s58, s14
	v_readlane_b32 s56, v252, 40
	s_addc_u32 s29, s59, 0
	v_lshl_add_u64 v[54:55], v[54:55], 0, s[82:83]
	v_readlane_b32 s57, v252, 41
	s_add_u32 s14, s56, s14
	v_lshl_add_u64 v[134:135], v[54:55], 0, v[8:9]
	s_addc_u32 s15, s57, 0
	v_lshlrev_b32_e32 v54, 2, v67
	v_mov_b32_e32 v55, v9
	v_lshl_add_u64 v[138:139], s[14:15], 0, v[54:55]
	s_add_u32 s14, s30, s82
	s_addc_u32 s15, s31, 0
	v_and_b32_e32 v61, 0xf0, v61
	v_lshl_or_b32 v68, v53, 6, v52
	v_lshl_or_b32 v53, v53, 7, v52
	v_and_b32_e32 v116, -8, v57
	v_and_b32_e32 v118, -8, v56
	v_lshl_add_u64 v[140:141], s[14:15], 0, v[8:9]
	s_sub_i32 s14, s26, s27
	v_add_u32_e32 v61, 16, v61
	v_lshl_add_u32 v66, v114, 1, 16
	v_sub_u32_e32 v70, v69, v112
	v_mul_lo_u32 v50, v50, s19
	v_ashrrev_i32_e32 v105, 31, v104
	v_ashrrev_i32_e32 v117, 31, v116
	v_ashrrev_i32_e32 v119, 31, v118
	v_ashrrev_i32_e32 v121, 31, v120
	v_mul_lo_u32 v56, v68, s21
	v_mul_lo_u32 v53, v53, s19
	v_add_u32_e32 v8, v51, v52
	s_sub_i32 s18, s14, 63
	s_add_i32 s14, s34, 64
	v_mov_b32_e32 v158, 0
	v_cmp_gt_u32_e64 s[40:41], 16, v114
	v_cmp_gt_i32_e64 s[42:43], 16, v102
	v_lshl_add_u64 v[124:125], v[104:105], 1, v[64:65]
	v_cmp_gt_i32_e64 s[44:45], 16, v106
	v_lshl_add_u64 v[128:129], v[116:117], 1, v[64:65]
	v_cmp_gt_i32_e64 s[46:47], 16, v108
	v_lshl_add_u64 v[132:133], v[118:119], 1, v[64:65]
	v_cmp_gt_i32_e64 s[48:49], 16, v110
	v_lshl_add_u64 v[136:137], v[120:121], 1, v[64:65]
	v_ashrrev_i32_e32 v107, 31, v106
	v_ashrrev_i32_e32 v109, 31, v108
	v_ashrrev_i32_e32 v111, 31, v110
	v_sub_u32_e32 v159, v8, v101
	v_add_u32_e32 v160, s14, v110
	v_add_u32_e32 v161, s14, v108
	v_add_u32_e32 v162, s14, v106
	v_add_u32_e32 v163, s14, v102
	v_add_u32_e32 v164, s14, v114
	v_mov_b32_e32 v8, 0xff800000
	s_mov_b32 s19, 0
	v_add_u32_e32 v165, v61, v71
	v_add_u32_e32 v166, v66, v60
	v_add_u32_e32 v167, v61, v72
	v_add_u32_e32 v168, v66, v59
	v_add_u32_e32 v169, v61, v73
	v_add_u32_e32 v170, v66, v50
	v_add_u32_e32 v171, v61, v74
	v_add_u32_e32 v172, v66, v58
	s_lshl_b32 s82, s20, 1
	v_add_u32_e32 v173, v69, v56
	v_add_u32_e32 v174, v70, v53
	s_mov_b32 s21, 0
	v_mov_b32_e32 v78, 0
	v_mov_b32_e32 v79, v158
	v_mov_b32_e32 v80, v158
	v_mov_b32_e32 v81, v158
	v_mov_b32_e32 v74, 0
	v_mov_b32_e32 v75, v158
	v_mov_b32_e32 v76, v158
	v_mov_b32_e32 v77, v158
	v_mov_b32_e32 v70, 0
	v_mov_b32_e32 v71, v158
	v_mov_b32_e32 v72, v158
	v_mov_b32_e32 v73, v158
	v_mov_b32_e32 v66, 0
	v_mov_b32_e32 v67, v158
	v_mov_b32_e32 v68, v158
	v_mov_b32_e32 v69, v158
	v_mov_b32_e32 v58, 0
	v_mov_b32_e32 v59, v158
	v_mov_b32_e32 v60, v158
	v_mov_b32_e32 v61, v158
	v_mov_b32_e32 v54, 0
	v_mov_b32_e32 v55, v158
	v_mov_b32_e32 v56, v158
	v_mov_b32_e32 v57, v158
	v_mov_b32_e32 v50, 0
	v_mov_b32_e32 v51, v158
	v_mov_b32_e32 v52, v158
	v_mov_b32_e32 v53, v158
	v_mov_b32_e32 v62, 0
	v_mov_b32_e32 v63, v158
	v_mov_b32_e32 v64, v158
	v_mov_b32_e32 v65, v158
	s_mov_b32 s26, 0xff800000
	v_readlane_b32 s53, v252, 37
	v_readlane_b32 s54, v252, 38
	v_readlane_b32 s55, v252, 39
	v_readlane_b32 s60, v252, 44
	v_readlane_b32 s61, v252, 45
	v_readlane_b32 s62, v252, 46
	v_readlane_b32 s63, v252, 47
	v_readlane_b32 s64, v252, 48
	v_readlane_b32 s65, v252, 49
	v_readlane_b32 s66, v252, 50
	v_readlane_b32 s67, v252, 51
	v_and_b32_e32 v236, 31, v114
	v_mul_u32_u24_e32 v237, 0x210, v102
	v_lshl_add_u32 v236, v236, 4, v237
	v_add_u32_e32 v236, 0x12800, v236
	v_mul_u32_u24_e32 v237, 0x210, v114
	v_lshrrev_b32_e32 v82, 1, v102
	v_lshl_add_u32 v237, v82, 4, v237
	v_add_u32_e32 v237, 0x12800, v237
.LBB0_352:
	s_and_b64 vcc, exec, s[38:39]
	s_cbranch_vccnz .Lattn_nobounce
	s_waitcnt vmcnt(0)
	ds_write_b128 v236, v[22:25]
	ds_write_b128 v236, v[30:33] offset:8448
	ds_write_b128 v236, v[38:41] offset:16896
	ds_write_b128 v236, v[46:49] offset:25344
	s_waitcnt lgkmcnt(0)
	s_barrier
	ds_read_b128 v[22:25], v237
	ds_read_b128 v[30:33], v237 offset:128
	ds_read_b128 v[38:41], v237 offset:256
	ds_read_b128 v[46:49], v237 offset:384
	s_waitcnt lgkmcnt(0)
	s_add_i32 s20, s21, 1
	s_cmp_ge_i32 s20, s25
	s_branch .Lattn_stage

; #define LAS __attribute__((address_space(3)))
; __device__ __forceinline__ void attn_item(const Params& P, int l, LAS unsigned char* lds, int item, const int wv) {
;     ...
;         for (int i = 0; i < 4; ++i) {
;             { const int idx = tid + 512 * i, key = idx >> 5, hc = idx & 31, hh = hc >> 4, ch = hc & 15;
;               *(LAS u32x4*)(Kl + (hh * 64 + key) * 136 + 8 * ch) = kreg[i]; }
;             { const int idx = tid + 512 * i, key = idx & 63, hc = idx >> 6, hh = hc >> 4, ch = hc & 15; const u32x4 vv = vreg[i];
;               LAS bf16_t* d = Vt + (hh * 128 + 8 * ch) * 72 + key;
;               d[0 * 72] = (bf16_t)(vv.x & 0xffffu); d[1 * 72] = (bf16_t)(vv.x >> 16); d[2 * 72] = (bf16_t)(vv.y & 0xffffu); d[3 * 72] = (bf16_t)(vv.y >> 16);
;               d[4 * 72] = (bf16_t)(vv.z & 0xffffu); d[5 * 72] = (bf16_t)(vv.z >> 16); d[6 * 72] = (bf16_t)(vv.w & 0xffffu); d[7 * 72] = (bf16_t)(vv.w >> 16); }
;         }
;         if (jt + 1 < nkt) ATT_LOAD(jt + 1);
.Lattn_stage:
	s_waitcnt vmcnt(7)
	ds_write_b128 v165, v[18:21]
	s_waitcnt vmcnt(6)
	ds_write_b16 v166, v22 offset:34816
	ds_write_b16_d16_hi v166, v22 offset:34960
	ds_write_b16 v166, v23 offset:35104
	ds_write_b16_d16_hi v166, v23 offset:35248
	ds_write_b16 v166, v24 offset:35392
	ds_write_b16_d16_hi v166, v24 offset:35536
	ds_write_b16 v166, v25 offset:35680
	ds_write_b16_d16_hi v166, v25 offset:35824
	s_waitcnt vmcnt(5)
	ds_write_b128 v167, v[26:29]
	s_waitcnt vmcnt(4)
	ds_write_b16 v168, v30 offset:34816
	ds_write_b16_d16_hi v168, v30 offset:34960
	ds_write_b16 v168, v31 offset:35104
	ds_write_b16_d16_hi v168, v31 offset:35248
	ds_write_b16 v168, v32 offset:35392
	ds_write_b16_d16_hi v168, v32 offset:35536
	ds_write_b16 v168, v33 offset:35680
	ds_write_b16_d16_hi v168, v33 offset:35824
	s_waitcnt vmcnt(3)
	ds_write_b128 v169, v[34:37]
	s_waitcnt vmcnt(2)
	ds_write_b16 v170, v38 offset:34816
	ds_write_b16_d16_hi v170, v38 offset:34960
	ds_write_b16 v170, v39 offset:35104
	ds_write_b16_d16_hi v170, v39 offset:35248
	ds_write_b16 v170, v40 offset:35392
	ds_write_b16_d16_hi v170, v40 offset:35536
	ds_write_b16 v170, v41 offset:35680
	ds_write_b16_d16_hi v170, v41 offset:35824
	s_waitcnt vmcnt(0)
	ds_write_b128 v171, v[42:45]
	s_waitcnt vmcnt(0)
	ds_write_b16 v172, v46 offset:34816
	ds_write_b16_d16_hi v172, v46 offset:34960
	ds_write_b16 v172, v47 offset:35104
	ds_write_b16_d16_hi v172, v47 offset:35248
	ds_write_b16 v172, v48 offset:35392
	ds_write_b16_d16_hi v172, v48 offset:35536
	ds_write_b16 v172, v49 offset:35680
	ds_write_b16_d16_hi v172, v49 offset:35824
	s_cbranch_scc1 .LBB0_376
	s_and_b64 vcc, exec, s[38:39]
	s_mov_b64 s[14:15], -1
	s_cbranch_vccnz .LBB0_355
	v_add_u32_e32 v20, s19, v164
	v_mov_b64_e32 v[18:19], s[30:31]
	v_mad_u64_u32 v[18:19], s[14:15], v20, s13, v[18:19]
	v_lshl_add_u64 v[18:19], v[18:19], 0, s[82:83]
	s_mov_b64 s[14:15], 0x1000
	v_lshl_add_u64 v[42:43], v[18:19], 0, s[14:15]
	v_add_u32_e32 v18, s19, v163
	v_add_u32_e32 v26, s19, v162
	v_add_u32_e32 v34, s19, v161
	v_add_u32_e32 v44, s19, v160
	v_mad_i64_i32 v[18:19], s[14:15], v18, s13, v[140:141]
	v_lshl_add_u64 v[22:23], v[104:105], 1, v[42:43]
	v_mad_i64_i32 v[26:27], s[14:15], v26, s13, v[140:141]
	v_lshl_add_u64 v[30:31], v[116:117], 1, v[42:43]
	v_mad_i64_i32 v[34:35], s[14:15], v34, s13, v[140:141]
	v_lshl_add_u64 v[38:39], v[118:119], 1, v[42:43]
	v_mad_i64_i32 v[44:45], s[14:15], v44, s13, v[140:141]
	v_lshl_add_u64 v[46:47], v[120:121], 1, v[42:43]
	s_mov_b64 s[14:15], 0x1000
	v_lshl_add_u64 v[22:23], v[18:19], 0, s[14:15]
	v_lshl_add_u64 v[30:31], v[26:27], 0, s[14:15]
	v_lshl_add_u64 v[38:39], v[34:35], 0, s[14:15]
	v_lshl_add_u64 v[46:47], v[44:45], 0, s[14:15]
	global_load_dwordx4 v[18:21], v[18:19], off offset:2048
	s_nop 0
	global_load_dwordx4 v[22:25], v[22:23], off
	s_nop 0
	global_load_dwordx4 v[26:29], v[26:27], off offset:2048
	s_nop 0
	global_load_dwordx4 v[30:33], v[30:31], off
	s_nop 0
	global_load_dwordx4 v[34:37], v[34:35], off offset:2048
	s_nop 0
	global_load_dwordx4 v[38:41], v[38:39], off
	s_nop 0
	global_load_dwordx4 v[42:45], v[44:45], off offset:2048
	s_nop 0
	global_load_dwordx4 v[46:49], v[46:47], off
	s_mov_b64 s[14:15], 0
